# mixer C walk: need-more flag reads issued right behind the per-tile barrier and checked after the next tile's loads and fragment reads are issued (flag latency off the barrier-to-compute path)
# baseline (speedup 1.0000x reference)
.Lcc_compute:
	v_mfma_f32_16x16x32_bf16 v[84:87], v[84:87], v[16:19], 0
	v_mfma_f32_16x16x32_bf16 v[100:103], v[100:103], v[16:19], 0
	v_mfma_f32_16x16x32_bf16 v[68:71], v[68:71], v[20:23], v[100:103]
	v_mfma_f32_16x16x32_bf16 v[56:59], v[56:59], v[20:23], v[84:87]
	v_mfma_f32_16x16x32_bf16 v[92:95], v[92:95], v[16:19], 0
	s_nop 5
	v_mul_f32_e32 v82, 0x3e000000, v68
	v_mul_f32_e64 v84, |v82|, s80
	v_exp_f32_e32 v84, v84
	v_max_f32_e32 v82, 0, v82
	v_mfma_f32_16x16x32_bf16 v[60:63], v[60:63], v[20:23], v[92:95]
	v_add_f32_e32 v84, 1.0, v84
	v_log_f32_e32 v84, v84
	v_mfma_f32_16x16x32_bf16 v[96:99], v[96:99], v[16:19], 0
	v_fmac_f32_e32 v82, 0x3f317218, v84
	v_fma_f32 v68, v68, s70, -v82
	v_cndmask_b32_e32 v92, v241, v68, vcc
	v_sub_f32_e32 v68, 0, v82
	v_add_u32_e32 v82, 1, v91
	v_cndmask_b32_e32 v68, 0, v68, vcc
	v_cmp_lt_i32_e32 vcc, v82, v72
	v_mul_f32_e32 v82, 0x3e000000, v69
	v_mul_f32_e64 v84, |v82|, s80
	v_exp_f32_e32 v84, v84
	v_max_f32_e32 v82, 0, v82
	v_mfma_f32_16x16x32_bf16 v[64:67], v[64:67], v[20:23], v[96:99]
	v_add_f32_e32 v84, 1.0, v84
	v_log_f32_e32 v84, v84
	s_nop 0
	v_fmac_f32_e32 v82, 0x3f317218, v84
	v_fma_f32 v69, v69, s70, -v82
	v_cndmask_b32_e32 v98, v241, v69, vcc
	v_add_u32_e32 v69, 2, v91
	v_cndmask_b32_e64 v97, 0, -v82, vcc
	v_cmp_lt_i32_e32 vcc, v69, v72
	v_mul_f32_e32 v69, 0x3e000000, v70
	v_mul_f32_e64 v82, |v69|, s80
	v_exp_f32_e32 v82, v82
	v_max_f32_e32 v69, 0, v69
	v_add_f32_e32 v68, v97, v68
	v_add_f32_e32 v82, 1.0, v82
	v_log_f32_e32 v82, v82
	s_nop 0
	v_fmac_f32_e32 v69, 0x3f317218, v82
	v_cndmask_b32_e64 v99, 0, -v69, vcc
	v_fma_f32 v69, v70, s70, -v69
	v_cndmask_b32_e32 v100, v241, v69, vcc
	v_add_u32_e32 v69, 3, v91
	v_cmp_lt_i32_e32 vcc, v69, v72
	v_mul_f32_e32 v69, 0x3e000000, v71
	v_mul_f32_e64 v70, |v69|, s80
	v_exp_f32_e32 v70, v70
	v_max_f32_e32 v69, 0, v69
	v_add_f32_e32 v68, v99, v68
	v_add_f32_e32 v70, 1.0, v70
	v_log_f32_e32 v70, v70
	s_nop 0
	v_fmac_f32_e32 v69, 0x3f317218, v70
	v_cndmask_b32_e64 v101, 0, -v69, vcc
	v_fma_f32 v69, v71, s70, -v69
	v_cndmask_b32_e32 v102, v241, v69, vcc
	v_add_u32_e32 v69, 16, v91
	v_cmp_lt_i32_e32 vcc, v69, v72
	v_mul_f32_e32 v69, 0x3e000000, v64
	v_mul_f32_e64 v71, |v69|, s80
	v_exp_f32_e32 v71, v71
	v_max_f32_e32 v69, 0, v69
	v_add_f32_e32 v93, v101, v68
	ds_bpermute_b32 v94, v88, v93
	v_add_f32_e32 v71, 1.0, v71
	v_log_f32_e32 v71, v71
	ds_bpermute_b32 v95, v89, v93
	ds_bpermute_b32 v96, v90, v93
	v_fmac_f32_e32 v69, 0x3f317218, v71
	v_fma_f32 v64, v64, s70, -v69
	v_cndmask_b32_e32 v103, v241, v64, vcc
	v_sub_f32_e32 v64, 0, v69
	v_add_u32_e32 v69, 17, v91
	v_cndmask_b32_e32 v64, 0, v64, vcc
	v_cmp_lt_i32_e32 vcc, v69, v72
	v_mul_f32_e32 v69, 0x3e000000, v65
	v_mul_f32_e64 v71, |v69|, s80
	v_exp_f32_e32 v71, v71
	v_max_f32_e32 v69, 0, v69
	v_add_f32_e32 v71, 1.0, v71
	v_log_f32_e32 v71, v71
	s_nop 0
	v_fmac_f32_e32 v69, 0x3f317218, v71
	v_fma_f32 v65, v65, s70, -v69
	v_cndmask_b32_e32 v105, v241, v65, vcc
	v_add_u32_e32 v65, 18, v91
	v_cndmask_b32_e64 v104, 0, -v69, vcc
	v_cmp_lt_i32_e32 vcc, v65, v72
	v_mul_f32_e32 v65, 0x3e000000, v66
	v_mul_f32_e64 v69, |v65|, s80
	v_exp_f32_e32 v69, v69
	v_max_f32_e32 v65, 0, v65
	v_add_f32_e32 v64, v104, v64
	v_add_f32_e32 v69, 1.0, v69
	v_log_f32_e32 v69, v69
	s_nop 0
	v_fmac_f32_e32 v65, 0x3f317218, v69
	v_cndmask_b32_e64 v106, 0, -v65, vcc
	v_fma_f32 v65, v66, s70, -v65
	v_cndmask_b32_e32 v107, v241, v65, vcc
	v_add_u32_e32 v65, 19, v91
	v_cmp_lt_i32_e32 vcc, v65, v72
	v_mul_f32_e32 v65, 0x3e000000, v67
	v_mul_f32_e64 v66, |v65|, s80
	v_exp_f32_e32 v66, v66
	v_max_f32_e32 v65, 0, v65
	v_add_f32_e32 v64, v106, v64
	v_add_f32_e32 v66, 1.0, v66
	v_log_f32_e32 v66, v66
	s_nop 0
	v_fmac_f32_e32 v65, 0x3f317218, v66
	v_cndmask_b32_e64 v108, 0, -v65, vcc
	v_fma_f32 v65, v67, s70, -v65
	v_add_f32_e32 v64, v108, v64
	v_cndmask_b32_e32 v109, v241, v65, vcc
	s_waitcnt lgkmcnt(0)
	v_cndmask_b32_e64 v70, 0, v94, s[6:7]
	v_cndmask_b32_e64 v84, 0, v95, s[8:9]
	v_cndmask_b32_e64 v68, 0, v96, s[10:11]
	ds_bpermute_b32 v208, v88, v64
	ds_bpermute_b32 v209, v89, v64
	ds_bpermute_b32 v85, v90, v64
	v_add_u32_e32 v65, 32, v91
	v_cmp_lt_i32_e32 vcc, v65, v72
	v_mul_f32_e32 v65, 0x3e000000, v60
	v_mul_f32_e64 v67, |v65|, s80
	v_exp_f32_e32 v67, v67
	v_max_f32_e32 v65, 0, v65
	v_add_f32_e32 v67, 1.0, v67
	v_log_f32_e32 v67, v67
	s_nop 0
	v_fmac_f32_e32 v65, 0x3f317218, v67
	v_fma_f32 v60, v60, s70, -v65
	v_cndmask_b32_e32 v110, v241, v60, vcc
	v_sub_f32_e32 v60, 0, v65
	v_add_u32_e32 v65, 33, v91
	v_cndmask_b32_e32 v60, 0, v60, vcc
	v_cmp_lt_i32_e32 vcc, v65, v72
	v_mul_f32_e32 v65, 0x3e000000, v61
	v_mul_f32_e64 v67, |v65|, s80
	v_exp_f32_e32 v67, v67
	v_max_f32_e32 v65, 0, v65
	v_add_f32_e32 v67, 1.0, v67
	v_log_f32_e32 v67, v67
	s_nop 0
	v_fmac_f32_e32 v65, 0x3f317218, v67
	v_fma_f32 v61, v61, s70, -v65
	v_cndmask_b32_e32 v112, v241, v61, vcc
	v_add_u32_e32 v61, 34, v91
	v_cndmask_b32_e64 v111, 0, -v65, vcc
	v_cmp_lt_i32_e32 vcc, v61, v72
	v_mul_f32_e32 v61, 0x3e000000, v62
	v_mul_f32_e64 v65, |v61|, s80
	v_exp_f32_e32 v65, v65
	v_max_f32_e32 v61, 0, v61
	v_add_f32_e32 v60, v111, v60
	v_add_f32_e32 v65, 1.0, v65
	v_log_f32_e32 v65, v65
	s_nop 0
	v_fmac_f32_e32 v61, 0x3f317218, v65
	v_cndmask_b32_e64 v113, 0, -v61, vcc
	v_fma_f32 v61, v62, s70, -v61
	v_cndmask_b32_e32 v114, v241, v61, vcc
	v_add_u32_e32 v61, 35, v91
	v_cmp_lt_i32_e32 vcc, v61, v72
	v_mul_f32_e32 v61, 0x3e000000, v63
	v_mul_f32_e64 v62, |v61|, s80
	v_exp_f32_e32 v62, v62
	v_max_f32_e32 v61, 0, v61
	v_add_f32_e32 v60, v113, v60
	v_add_f32_e32 v62, 1.0, v62
	v_log_f32_e32 v62, v62
	s_nop 0
	v_fmac_f32_e32 v61, 0x3f317218, v62
	v_cndmask_b32_e64 v117, 0, -v61, vcc
	v_fma_f32 v61, v63, s70, -v61
	v_add_f32_e32 v60, v117, v60
	v_cndmask_b32_e32 v118, v241, v61, vcc
	s_waitcnt lgkmcnt(0)
	v_add_f32_e32 v64, v64, v208
	v_cndmask_b32_e64 v66, 0, v208, s[6:7]
	v_add_f32_e32 v71, v64, v209
	v_cndmask_b32_e64 v86, 0, v209, s[8:9]
	v_cndmask_b32_e64 v64, 0, v85, s[10:11]
	ds_bpermute_b32 v211, v88, v60
	ds_bpermute_b32 v212, v89, v60
	ds_bpermute_b32 v87, v90, v60
	v_add_u32_e32 v61, 48, v91
	v_cmp_lt_i32_e32 vcc, v61, v72
	v_mul_f32_e32 v61, 0x3e000000, v56
	v_mul_f32_e64 v63, |v61|, s80
	v_exp_f32_e32 v63, v63
	v_max_f32_e32 v61, 0, v61
	v_add_f32_e32 v63, 1.0, v63
	v_log_f32_e32 v63, v63
	s_nop 0
	v_fmac_f32_e32 v61, 0x3f317218, v63
	v_fma_f32 v56, v56, s70, -v61
	v_cndmask_b32_e32 v119, v241, v56, vcc
	v_sub_f32_e32 v56, 0, v61
	v_add_u32_e32 v61, 49, v91
	v_cndmask_b32_e32 v56, 0, v56, vcc
	v_cmp_lt_i32_e32 vcc, v61, v72
	v_mul_f32_e32 v61, 0x3e000000, v57
	v_mul_f32_e64 v63, |v61|, s80
	v_exp_f32_e32 v63, v63
	v_max_f32_e32 v61, 0, v61
	v_add_f32_e32 v63, 1.0, v63
	v_log_f32_e32 v63, v63
	s_nop 0
	v_fmac_f32_e32 v61, 0x3f317218, v63
	v_fma_f32 v57, v57, s70, -v61
	v_cndmask_b32_e32 v121, v241, v57, vcc
	v_add_u32_e32 v57, 50, v91
	v_cndmask_b32_e64 v120, 0, -v61, vcc
	v_cmp_lt_i32_e32 vcc, v57, v72
	v_mul_f32_e32 v57, 0x3e000000, v58
	v_mul_f32_e64 v61, |v57|, s80
	v_exp_f32_e32 v61, v61
	v_max_f32_e32 v57, 0, v57
	v_add_f32_e32 v56, v120, v56
	v_add_f32_e32 v61, 1.0, v61
	v_log_f32_e32 v61, v61
	s_nop 0
	v_fmac_f32_e32 v57, 0x3f317218, v61
	v_cndmask_b32_e64 v122, 0, -v57, vcc
	v_fma_f32 v57, v58, s70, -v57
	v_cndmask_b32_e32 v123, v241, v57, vcc
	v_add_u32_e32 v57, 51, v91
	v_cmp_lt_i32_e32 vcc, v57, v72
	v_mul_f32_e32 v57, 0x3e000000, v59
	v_mul_f32_e64 v58, |v57|, s80
	v_exp_f32_e32 v58, v58
	v_max_f32_e32 v57, 0, v57
	v_add_f32_e32 v56, v122, v56
	v_add_f32_e32 v58, 1.0, v58
	v_log_f32_e32 v58, v58
	s_nop 0
	v_fmac_f32_e32 v57, 0x3f317218, v58
	v_cndmask_b32_e64 v124, 0, -v57, vcc
	v_fma_f32 v57, v59, s70, -v57
	v_add_f32_e32 v56, v124, v56
	v_cndmask_b32_e32 v125, v241, v57, vcc
	s_waitcnt lgkmcnt(0)
	v_add_f32_e32 v60, v60, v211
	v_add_f32_e32 v67, v60, v212
	v_cndmask_b32_e64 v60, 0, v211, s[6:7]
	v_cndmask_b32_e64 v62, 0, v212, s[8:9]
	v_cndmask_b32_e64 v82, 0, v87, s[10:11]
	ds_bpermute_b32 v57, v88, v56
	ds_bpermute_b32 v58, v89, v56
	ds_bpermute_b32 v63, v90, v56
	s_waitcnt lgkmcnt(2)
	v_add_f32_e32 v56, v56, v57
	s_waitcnt lgkmcnt(1)
	v_add_f32_e32 v61, v56, v58
	v_cndmask_b32_e64 v56, 0, v57, s[6:7]
	v_cndmask_b32_e64 v57, 0, v58, s[8:9]
	v_add_f32_e32 v56, v56, v57
	s_waitcnt lgkmcnt(0)
	v_cndmask_b32_e64 v57, 0, v63, s[10:11]
	v_add_f32_e32 v56, v56, v57
	v_add_f32_e32 v126, v83, v56
	v_pk_add_f32 v[56:57], v[60:61], v[62:63]
	v_pk_add_f32 v[58:59], v[66:67], v[86:87]
	v_pk_add_f32 v[60:61], v[56:57], v[82:83]
	v_add_f32_e32 v82, v124, v126
	v_mov_b32_e32 v65, v61
	v_pk_add_f32 v[62:63], v[58:59], v[64:65]
	v_add_f32_e32 v56, v60, v61
	v_pk_add_f32 v[60:61], v[70:71], v[84:85]
	v_mov_b32_e32 v69, v63
	v_add_f32_e32 v58, v62, v63
	v_pk_add_f32 v[62:63], v[60:61], v[68:69]
	v_add_f32_e32 v65, v109, v58
	v_add_f32_e32 v60, v62, v63
	v_add_f32_e32 v62, v102, v60
	v_mul_f32_e32 v62, 0x3fb8aa3b, v62
	v_add_f32_e32 v60, v101, v60
	v_exp_f32_e32 v63, v62
	v_add_f32_e32 v62, v100, v60
	v_add_f32_e32 v58, v108, v58
	v_mul_f32_e32 v62, 0x3fb8aa3b, v62
	v_add_f32_e32 v60, v99, v60
	v_add_f32_e32 v66, v107, v58
	v_add_f32_e32 v58, v106, v58
	v_exp_f32_e32 v64, v62
	v_add_f32_e32 v62, v98, v60
	v_add_f32_e32 v60, v97, v60
	v_add_f32_e32 v67, v105, v58
	v_add_f32_e32 v58, v104, v58
	v_add_f32_e32 v60, v92, v60
	v_add_f32_e32 v58, v103, v58
	v_mul_f32_e32 v62, 0x3fb8aa3b, v62
	v_mul_f32_e32 v60, 0x3fb8aa3b, v60
	v_mul_f32_e32 v65, 0x3fb8aa3b, v65
	v_mul_f32_e32 v66, 0x3fb8aa3b, v66
	v_mul_f32_e32 v67, 0x3fb8aa3b, v67
	v_mul_f32_e32 v58, 0x3fb8aa3b, v58
	v_add_f32_e32 v68, v118, v56
	v_add_f32_e32 v56, v117, v56
	v_exp_f32_e32 v62, v62
	v_exp_f32_e32 v60, v60
	v_exp_f32_e32 v65, v65
	v_exp_f32_e32 v66, v66
	v_exp_f32_e32 v67, v67
	v_exp_f32_e32 v58, v58
	v_add_f32_e32 v69, v114, v56
	v_add_f32_e32 v56, v113, v56
	v_add_f32_e32 v84, v123, v82
	v_add_f32_e32 v82, v122, v82
	v_add_f32_e32 v70, v112, v56
	v_add_f32_e32 v56, v111, v56
	v_add_f32_e32 v85, v121, v82
	v_add_f32_e32 v82, v120, v82
	v_add_f32_e32 v56, v110, v56
	v_add_f32_e32 v71, v125, v126
	v_add_f32_e32 v82, v119, v82
	v_mul_f32_e32 v68, 0x3fb8aa3b, v68
	v_mul_f32_e32 v69, 0x3fb8aa3b, v69
	v_mul_f32_e32 v70, 0x3fb8aa3b, v70
	v_mul_f32_e32 v56, 0x3fb8aa3b, v56
	v_mul_f32_e32 v71, 0x3fb8aa3b, v71
	v_mul_f32_e32 v84, 0x3fb8aa3b, v84
	v_mul_f32_e32 v85, 0x3fb8aa3b, v85
	v_mul_f32_e32 v82, 0x3fb8aa3b, v82
	v_exp_f32_e32 v68, v68
	v_exp_f32_e32 v69, v69
	v_exp_f32_e32 v70, v70
	v_exp_f32_e32 v56, v56
	v_exp_f32_e32 v71, v71
	v_exp_f32_e32 v84, v84
	v_exp_f32_e32 v85, v85
	v_exp_f32_e32 v82, v82
	v_cvt_pk_bf16_f32 v62, v60, v62
	v_cvt_pk_bf16_f32 v63, v64, v63
	v_cvt_pk_bf16_f32 v64, v58, v67
	v_cvt_pk_bf16_f32 v65, v66, v65
	v_cvt_pk_bf16_f32 v66, v56, v70
	v_cvt_pk_bf16_f32 v67, v69, v68
	v_mfma_f32_16x16x32_bf16 v[0:3], v[52:55], v[62:65], v[0:3]
	v_cvt_pk_bf16_f32 v68, v82, v85
	v_cvt_pk_bf16_f32 v69, v84, v71
	v_mfma_f32_16x16x32_bf16 v[4:7], v[44:47], v[62:65], v[4:7]
	v_mfma_f32_16x16x32_bf16 v[8:11], v[36:39], v[62:65], v[8:11]
	v_mfma_f32_16x16x32_bf16 v[12:15], v[28:31], v[62:65], v[12:15]
	v_mfma_f32_16x16x32_bf16 v[0:3], v[48:51], v[66:69], v[0:3]
	v_mfma_f32_16x16x32_bf16 v[4:7], v[40:43], v[66:69], v[4:7]
	v_mfma_f32_16x16x32_bf16 v[8:11], v[32:35], v[66:69], v[8:11]
	v_mfma_f32_16x16x32_bf16 v[12:15], v[24:27], v[66:69], v[12:15]
	s_cbranch_scc0 .Lcc_last
	v_add_f32_e32 v24, v93, v94
	v_add_f32_e32 v24, v24, v95
	v_add_f32_e32 v24, v24, v96
	v_add_f32_e32 v24, v24, v61
	v_add_f32_e32 v24, v24, v59
	v_add_f32_e32 v24, v24, v57
	v_add_f32_e32 v83, v83, v24
	v_cmp_lt_f32_e32 vcc, s38, v83
	s_cbranch_vccnz .Lcc_after

.Lcc_nostore:
	s_xor_b32 s20, s15, 1
	v_mov_b32_e32 v135, s20
	v_add_u32_e32 v134, s21, v156
	ds_write_b32 v134, v135 offset:8448
	s_waitcnt lgkmcnt(0)
	s_barrier
	s_cmp_eq_u32 s13, 0
	s_cbranch_scc1 .LBB0_402
	v_mov_b32_e32 v134, s21
	ds_read_b128 v[148:151], v134 offset:8448
	ds_read_b128 v[152:155], v134 offset:8464
	s_add_i32 s13, s13, -1
	s_xor_b32 s14, s14, 0x5000
	s_xor_b32 s21, s21, 32
	s_cmp_eq_u32 s13, 0
	s_cbranch_scc1 .Lcf_noload
	v_subrev_co_u32_e32 v130, vcc, 0x2000, v130
	s_nop 1
	v_subbrev_co_u32_e32 v131, vcc, 0, v131, vcc
	v_subrev_co_u32_e32 v132, vcc, 0x80, v132
	s_nop 1
	v_subbrev_co_u32_e32 v133, vcc, 0, v133, vcc
	global_load_dwordx4 v[140:143], v[130:131], off
	global_load_dwordx4 v[144:147], v[132:133], off
.Lcf_noload:
	s_cmp_gt_i32 s13, s12
	s_cbranch_scc1 .Lcf_idle
	s_cmp_lg_u32 s15, 0
	s_cbranch_scc1 .Lcf_idle
	v_add_u32_e32 v135, s14, v127
	ds_read_b128 v[100:103], v135 offset:16384
	ds_read_b128 v[68:71], v135 offset:16448
	ds_read_b128 v[96:99], v135 offset:18944
	ds_read_b128 v[64:67], v135 offset:19008
	ds_read_b128 v[92:95], v135 offset:21504
	ds_read_b128 v[60:63], v135 offset:21568
	ds_read_b128 v[84:87], v135 offset:24064
	ds_read_b128 v[56:59], v135 offset:24128
	ds_read_b128 v[52:55], v135 offset:26624
	ds_read_b128 v[48:51], v135 offset:26688
	ds_read_b128 v[44:47], v135 offset:29184
	ds_read_b128 v[40:43], v135 offset:29248
	ds_read_b128 v[36:39], v135 offset:31744
	ds_read_b128 v[32:35], v135 offset:31808
	ds_read_b128 v[28:31], v135 offset:34304
	ds_read_b128 v[24:27], v135 offset:34368
	s_lshl_b32 s19, s13, 6
	v_add_u32_e32 v91, s19, v116
	v_cmp_lt_i32_e32 vcc, v91, v72
	s_waitcnt lgkmcnt(8)
	v_or3_b32 v148, v148, v149, v150
	v_or3_b32 v148, v148, v151, v152
	v_or3_b32 v148, v148, v153, v154
	v_or_b32_e32 v148, v148, v155
	s_nop 0
	v_readfirstlane_b32 s20, v148
	s_cmp_eq_u32 s20, 0
	s_cbranch_scc1 .LBB0_402
	s_cmp_lg_u32 s13, 0
	s_branch .Lcc_compute
.Lcf_idle:
	s_waitcnt lgkmcnt(0)
	v_or3_b32 v148, v148, v149, v150
	v_or3_b32 v148, v148, v151, v152
	v_or3_b32 v148, v148, v153, v154
	v_or_b32_e32 v148, v148, v155
	s_nop 0
	v_readfirstlane_b32 s20, v148
	s_cmp_eq_u32 s20, 0
	s_cbranch_scc1 .LBB0_402
	s_branch .Lcc_after
